# one static s_setprio 1 for waves 4-7 at kernel entry (all per-phase flips already removed)
# baseline (speedup 1.0000x reference)
_Z10hybrid_fwd4Args:
	s_mov_b32 s87, s2
	s_load_dwordx2 s[36:37], s[0:1], 0x108
	s_load_dword s2, s[0:1], 0x110
	v_and_b32_e32 v1, 0x3ff, v0
	v_cmp_eq_u32_e32 vcc, 0, v1
	v_readfirstlane_b32 s92, v1
	s_waitcnt lgkmcnt(0)
	s_nop 3
	s_cmp_lt_u32 s92, 0x100
	s_cbranch_scc1 .Lprio_skip
	s_setprio 1
.Lprio_skip:
	v_writelane_b32 v254, s2, 0
	s_nop 1
	v_writelane_b32 v254, s3, 1
	s_add_u32 s2, s0, 0x110
	v_writelane_b32 v254, s0, 2
	s_addc_u32 s3, s1, 0
	s_nop 0
	v_writelane_b32 v254, s1, 3
	s_and_saveexec_b64 s[0:1], vcc
	s_cbranch_execz .LBB0_3
	s_add_i32 s6, 0, 0x23e80
	v_mov_b32_e32 v2, 0
	v_mov_b32_e32 v3, s6
	s_add_i32 s6, 0, 0x23e84
	s_mov_b64 s[4:5], exec
	ds_write_b32 v3, v2
	v_mov_b32_e32 v3, s6
	ds_write_b32 v3, v2
	v_mbcnt_lo_u32_b32 v2, s4, 0
	v_mbcnt_hi_u32_b32 v2, s5, v2
	v_cmp_eq_u32_e32 vcc, 0, v2
	s_getreg_b32 s6, hwreg(HW_REG_XCC_ID, 0, 4)
	s_and_b64 s[8:9], exec, vcc
	s_mov_b64 exec, s[8:9]
	s_cbranch_execz .LBB0_3
	v_readlane_b32 s8, v254, 2
	v_readlane_b32 s9, v254, 3
	s_load_dwordx2 s[8:9], s[8:9], 0x100
	s_lshl_b32 s6, s6, 8
	s_and_b32 s6, s6, 0xf00
	v_mov_b32_e32 v2, 0x8000
	s_waitcnt lgkmcnt(0)
	s_add_u32 s6, s8, s6
	s_addc_u32 s7, s9, 0
	s_bcnt1_i32_b64 s4, s[4:5]
	v_mov_b32_e32 v3, s4
	global_atomic_add v2, v3, s[6:7] offset:1024
